# v8
# speedup vs baseline: 1.0196x; 1.0048x over previous
.LBB0_121:
	v_add_u32_e32 v24, s33, v0
	v_ashrrev_i32_e32 v48, 4, v24
	v_and_b32_e32 v57, 63, v0
	v_and_b32_e32 v0, 0xfffff0, v48
	v_lshlrev_b32_e32 v5, 1, v48
	v_lshlrev_b32_e32 v4, 3, v24
	v_and_or_b32 v0, v5, 8, v0
	v_and_b32_e32 v182, 0x78, v4
	v_lshrrev_b32_e32 v5, 1, v48
	v_lshrrev_b32_e32 v0, 1, v0
	v_bfe_u32 v6, v4, 5, 2
	v_and_b32_e32 v7, 3, v48
	v_or_b32_e32 v0, v0, v6
	v_and_or_b32 v5, v5, 4, v7
	v_lshlrev_b32_e32 v180, 1, v182
	v_lshlrev_b32_e32 v0, 9, v0
	v_lshlrev_b32_e32 v5, 6, v5
	v_and_b32_e32 v7, 48, v180
	v_or3_b32 v25, v0, v5, v7
	v_add_u32_e32 v0, 32, v48
	v_and_b32_e32 v8, 0xfffff0, v0
	v_lshlrev_b32_e32 v9, 1, v0
	v_and_or_b32 v8, v9, 8, v8
	v_lshrrev_b32_e32 v8, 1, v8
	v_or_b32_e32 v6, v8, v6
	v_lshlrev_b32_e32 v6, 9, v6
	v_or3_b32 v26, v6, v5, v7
	v_lshlrev_b32_e32 v6, 4, v57
	v_lshlrev_b32_e32 v5, 3, v57
	v_and_b32_e32 v6, 0xc0, v6
	v_lshlrev_b32_e32 v7, 1, v57
	v_and_or_b32 v6, v5, 24, v6
	v_and_b32_e32 v7, 32, v7
	v_and_b32_e32 v5, 0x100, v5
	v_and_b32_e32 v188, 56, v4
	v_or3_b32 v58, v6, v7, v5
	v_and_b32_e32 v8, 0x70, v4
	global_load_dwordx4 v[4:7], v[2:3], off offset:256
	s_lshr_b32 s25, s27, 6
	s_lshl_b64 s[8:9], s[36:37], 12
	v_readlane_b32 s4, v255, 7
	s_add_u32 s6, s4, s8
	v_readlane_b32 s4, v255, 8
	s_addc_u32 s7, s4, s9
	s_lshl_b32 s4, s85, 8
	s_ashr_i32 s5, s4, 31
	s_lshl_b64 s[20:21], s[4:5], 1
	s_add_u32 s6, s6, s20
	s_addc_u32 s7, s7, s21
	s_add_u32 s4, s94, s20
	s_addc_u32 s5, s95, s21
	s_lshl_b64 s[10:11], s[36:37], 7
	v_readlane_b32 s22, v255, 5
	s_add_u32 s22, s22, s10
	v_readlane_b32 s23, v255, 6
	s_addc_u32 s23, s23, s11
	s_add_u32 s27, s4, 0x100
	s_addc_u32 s66, s5, 0
	s_cmp_lg_u32 0, -1
	s_cselect_b32 s67, 0, 0
	s_add_i32 s36, 0, 0x14800
	v_lshl_add_u32 v59, v1, 7, s36
	v_xad_u32 v1, v186, v8, v59
	v_or_b32_e32 v62, 32, v186
	v_or_b32_e32 v61, 64, v186
	v_or_b32_e32 v60, 0x60, v186
	v_ashrrev_i32_e32 v49, 31, v48
	v_lshlrev_b64 v[50:51], 12, v[48:49]
	v_ashrrev_i32_e32 v27, 3, v24
	v_lshlrev_b32_e32 v194, 6, v27
	v_ashrrev_i32_e32 v195, 31, v194
	v_lshl_add_u64 v[18:19], v[194:195], 1, s[22:23]
	v_lshlrev_b32_e32 v22, 1, v188
	v_mov_b32_e32 v23, v181
	v_lshl_add_u64 v[54:55], v[18:19], 0, v[22:23]
	v_add_u32_e32 v211, 0, v25
	v_lshlrev_b64 v[190:191], 11, v[48:49]
	s_add_i32 s22, 0, 0x10000
	v_add_u32_e32 v212, 0, v26
	v_lshlrev_b32_e32 v63, 8, v56
	v_lshlrev_b32_e32 v76, 7, v56
	s_movk_i32 s23, 0x70
	s_mov_b32 s36, s37
	s_mov_b32 s38, s37
	s_mov_b32 s39, s37
	s_mov_b32 s40, s37
	s_mov_b32 s41, s37
	s_mov_b32 s42, s37
	s_mov_b32 s43, s37
	s_mov_b32 s44, s37
	s_mov_b32 s45, s37
	s_mov_b32 s46, s37
	s_mov_b32 s47, s37
	s_mov_b32 s48, s37
	s_mov_b32 s49, s37
	s_mov_b32 s50, s37
	s_mov_b32 s51, s37
	v_add_u32_e32 v187, s67, v58
	v_lshl_add_u32 v236, v56, 2, s30
	v_mov_b32_e32 v237, 0
	v_mov_b32_e32 v241, 1.0
	s_waitcnt vmcnt(0)
	ds_write_b128 v1, v[4:7]
	global_load_dwordx4 v[4:7], v[2:3], off offset:288
	v_xad_u32 v1, v62, v8, v59
	s_waitcnt vmcnt(0)
	ds_write_b128 v1, v[4:7]
	global_load_dwordx4 v[4:7], v[2:3], off offset:320
	v_xad_u32 v1, v61, v8, v59
	s_waitcnt vmcnt(0)
	ds_write_b128 v1, v[4:7]
	global_load_dwordx4 v[2:5], v[2:3], off offset:352
	v_xad_u32 v1, v60, v8, v59
	s_waitcnt vmcnt(0)
	ds_write_b128 v1, v[2:5]
	v_lshl_add_u64 v[2:3], s[6:7], 0, v[50:51]
	v_lshl_add_u64 v[10:11], v[2:3], 0, v[180:181]
	global_load_dwordx4 v[2:5], v[10:11], off offset:256
	v_ashrrev_i32_e32 v1, 31, v0
	v_lshlrev_b64 v[52:53], 12, v[0:1]
	v_lshl_add_u64 v[6:7], s[6:7], 0, v[52:53]
	v_lshl_add_u64 v[14:15], v[6:7], 0, v[180:181]
	global_load_dwordx4 v[6:9], v[14:15], off offset:256
	s_nop 0
	global_load_dwordx4 v[10:13], v[10:11], off
	s_nop 0
	global_load_dwordx4 v[14:17], v[14:15], off
	v_lshlrev_b64 v[192:193], 11, v[0:1]
	global_load_dwordx4 v[18:21], v[54:55], off
	s_waitcnt vmcnt(0)
	v_lshlrev_b32_e32 v0, 8, v0
	v_lshlrev_b32_e32 v1, 8, v48
	s_waitcnt vmcnt(4)
	ds_write_b128 v211, v[2:5]
	v_and_b32_e32 v2, 0x70, v24
	v_bitop3_b32 v0, v180, v0, v2 bitop3:0xde
	v_add_u32_e32 v214, 0, v0
	v_lshlrev_b32_e32 v0, 7, v27
	v_bitop3_b32 v1, v180, v1, v2 bitop3:0xde
	v_bitop3_b32 v49, v22, v0, v2 bitop3:0xde
	v_add_u32_e32 v213, 0, v1
	v_add_u32_e32 v0, s22, v49
	s_waitcnt vmcnt(3)
	ds_write_b128 v212, v[6:9]
	s_waitcnt vmcnt(2)
	ds_write_b128 v213, v[10:13] offset:32768
	s_waitcnt vmcnt(1)
	ds_write_b128 v214, v[14:17] offset:32768
	s_waitcnt vmcnt(0)
	ds_write_b128 v0, v[18:21]
	v_lshlrev_b32_e32 v0, 4, v56
	v_and_b32_e32 v72, 0x70, v0
	v_bitop3_b32 v0, v186, v63, v72 bitop3:0xde
	v_add_u32_e32 v215, 0, v0
	s_waitcnt lgkmcnt(0)
	s_barrier
	ds_read_b128 v[16:19], v215 offset:32768
	ds_read_b128 v[20:23], v215 offset:40960
	s_waitcnt lgkmcnt(1)
	v_mfma_f32_32x32x16_bf16 v[32:47], v[16:19], v[128:131], 0
	v_bitop3_b32 v64, v62, v63, v72 bitop3:0xde
	v_add_u32_e32 v216, 0, v64
	ds_read_b128 v[64:67], v216 offset:32768
	ds_read_b128 v[68:71], v216 offset:40960
	v_mov_b64_e32 v[0:1], s[36:37]
	v_add_u32_e32 v238, 0, v49
	v_mov_b64_e32 v[14:15], s[50:51]
	v_add_u32_e32 v239, 0x12000, v238
	s_waitcnt lgkmcnt(2)
	v_mfma_f32_32x32x16_bf16 v[16:31], v[20:23], v[128:131], 0
	v_mov_b64_e32 v[2:3], s[38:39]
	v_mov_b64_e32 v[4:5], s[40:41]
	v_mov_b64_e32 v[6:7], s[42:43]
	v_mov_b64_e32 v[8:9], s[44:45]
	v_mov_b64_e32 v[10:11], s[46:47]
	v_mov_b64_e32 v[12:13], s[48:49]
	s_brev_b32 s50, 63
	s_waitcnt lgkmcnt(1)
	v_mfma_f32_32x32x16_bf16 v[32:47], v[64:67], v[132:135], v[32:47]
	v_bitop3_b32 v64, v61, v63, v72 bitop3:0xde
	v_add_u32_e32 v217, 0, v64
	s_mov_b32 s36, 2
	s_movk_i32 s51, 0x7ff
	s_waitcnt lgkmcnt(0)
	v_mfma_f32_32x32x16_bf16 v[16:31], v[68:71], v[132:135], v[16:31]
	ds_read_b128 v[64:67], v217 offset:32768
	ds_read_b128 v[68:71], v217 offset:40960
	s_waitcnt lgkmcnt(1)
	v_mfma_f32_32x32x16_bf16 v[32:47], v[64:67], v[136:139], v[32:47]
	v_bitop3_b32 v64, v60, v63, v72 bitop3:0xde
	v_add_u32_e32 v218, 0, v64
	s_waitcnt lgkmcnt(0)
	v_mfma_f32_32x32x16_bf16 v[16:31], v[68:71], v[136:139], v[16:31]
	ds_read_b128 v[64:67], v218 offset:32768
	ds_read_b128 v[68:71], v218 offset:40960
	s_waitcnt lgkmcnt(1)
	v_mfma_f32_32x32x16_bf16 v[32:47], v[64:67], v[140:143], v[32:47]
	v_or_b32_e32 v64, 0x80, v186
	v_bitop3_b32 v64, v64, v63, v72 bitop3:0xde
	v_add_u32_e32 v219, 0, v64
	s_waitcnt lgkmcnt(0)
	v_mfma_f32_32x32x16_bf16 v[16:31], v[68:71], v[140:143], v[16:31]
	ds_read_b128 v[64:67], v219 offset:32768
	ds_read_b128 v[68:71], v219 offset:40960
	s_waitcnt lgkmcnt(1)
	v_mfma_f32_32x32x16_bf16 v[32:47], v[64:67], v[144:147], v[32:47]
	v_or_b32_e32 v64, 0xa0, v186
	v_bitop3_b32 v64, v64, v63, v72 bitop3:0xde
	v_add_u32_e32 v220, 0, v64
	s_waitcnt lgkmcnt(0)
	v_mfma_f32_32x32x16_bf16 v[16:31], v[68:71], v[144:147], v[16:31]
	ds_read_b128 v[64:67], v220 offset:32768
	ds_read_b128 v[68:71], v220 offset:40960
	s_waitcnt lgkmcnt(1)
	v_mfma_f32_32x32x16_bf16 v[32:47], v[64:67], v[148:151], v[32:47]
	v_or_b32_e32 v64, 0xc0, v186
	v_bitop3_b32 v64, v64, v63, v72 bitop3:0xde
	v_add_u32_e32 v221, 0, v64
	s_waitcnt lgkmcnt(0)
	v_mfma_f32_32x32x16_bf16 v[16:31], v[68:71], v[148:151], v[16:31]
	ds_read_b128 v[64:67], v221 offset:32768
	ds_read_b128 v[68:71], v221 offset:40960
	s_waitcnt lgkmcnt(1)
	v_mfma_f32_32x32x16_bf16 v[32:47], v[64:67], v[152:155], v[32:47]
	v_or_b32_e32 v64, 0xe0, v186
	v_bitop3_b32 v63, v64, v63, v72 bitop3:0xde
	v_add_u32_e32 v222, 0, v63
	v_lshlrev_b32_e32 v63, 3, v56
	v_and_b32_e32 v77, 0x70, v63
	v_bitop3_b32 v63, v186, v63, s23 bitop3:0x78
	v_bitop3_b32 v223, v186, v76, v77 bitop3:0xde
	s_waitcnt lgkmcnt(0)
	v_mfma_f32_32x32x16_bf16 v[16:31], v[68:71], v[152:155], v[16:31]
	ds_read_b128 v[64:67], v222 offset:32768
	ds_read_b128 v[68:71], v222 offset:40960
	v_add_u32_e32 v224, s22, v223
	v_add_u32_e32 v225, v59, v63
	v_bitop3_b32 v226, v62, v76, v77 bitop3:0xde
	v_add_u32_e32 v227, s22, v226
	v_bitop3_b32 v229, v61, v76, v77 bitop3:0xde
	v_add_u32_e32 v230, s22, v229
	s_waitcnt lgkmcnt(1)
	v_mfma_f32_32x32x16_bf16 v[32:47], v[64:67], v[156:159], v[32:47]
	s_movk_i32 s23, 0x60
	v_bitop3_b32 v232, v60, v76, v77 bitop3:0xde
	v_add_u32_e32 v233, s22, v232
	s_add_u32 s22, s6, 0x40100
	s_waitcnt lgkmcnt(0)
	v_mfma_f32_32x32x16_bf16 v[16:31], v[68:71], v[156:159], v[16:31]
	ds_read_b128 v[64:67], v224
	ds_read_b128 v[68:71], v224 offset:4096
	ds_read_b128 v[72:75], v225
	s_waitcnt lgkmcnt(0)
	v_mfma_f32_32x32x16_bf16 v[32:47], v[64:67], v[72:75], v[32:47]
	v_mfma_f32_32x32x16_bf16 v[16:31], v[68:71], v[72:75], v[16:31]
	v_bitop3_b32 v70, v186, v77, 32 bitop3:0x36
	v_add_u32_e32 v228, v59, v70
	ds_read_b128 v[62:65], v227
	ds_read_b128 v[66:69], v227 offset:4096
	ds_read_b128 v[70:73], v228
	s_waitcnt lgkmcnt(0)
	v_mfma_f32_32x32x16_bf16 v[32:47], v[62:65], v[70:73], v[32:47]
	v_mfma_f32_32x32x16_bf16 v[16:31], v[66:69], v[70:73], v[16:31]
	v_bitop3_b32 v70, v186, v77, 64 bitop3:0x36
	v_add_u32_e32 v231, v59, v70
	ds_read_b128 v[62:65], v230
	ds_read_b128 v[66:69], v230 offset:4096
	ds_read_b128 v[70:73], v231
	s_waitcnt lgkmcnt(0)
	v_mfma_f32_32x32x16_bf16 v[32:47], v[62:65], v[70:73], v[32:47]
	v_mfma_f32_32x32x16_bf16 v[16:31], v[66:69], v[70:73], v[16:31]
	v_bitop3_b32 v68, v186, v77, s23 bitop3:0x36
	v_add_u32_e32 v234, v59, v68
	ds_read_b128 v[60:63], v233
	ds_read_b128 v[64:67], v233 offset:4096
	ds_read_b128 v[68:71], v234
	s_addc_u32 s23, s7, 0
	s_add_u32 s6, s6, 0x40000
	s_addc_u32 s7, s7, 0
	s_waitcnt lgkmcnt(0)
	v_mfma_f32_32x32x16_bf16 v[32:47], v[60:63], v[68:71], v[32:47]
	s_addk_i32 s67, 0x4000
	v_add_u32_e32 v240, s67, v58
	s_add_u32 s38, s8, s20
	s_addc_u32 s39, s9, s21
	s_sub_i32 s40, 0, s25
	s_nop 6
	v_max_f32_e32 v59, v33, v33
	v_max_f32_e32 v60, v32, v32
	v_mfma_f32_32x32x16_bf16 v[16:31], v[64:67], v[68:71], v[16:31]
	v_max_f32_e32 v59, v60, v59
	v_max3_f32 v59, v59, v34, v35
	v_max3_f32 v59, v59, v36, v37
	v_max3_f32 v59, v59, v38, v39
	v_max3_f32 v59, v59, v40, v41
	v_max3_f32 v59, v59, v42, v43
	v_max3_f32 v59, v59, v44, v45
	v_max3_f32 v59, v59, v46, v47
	s_nop 3
	v_max3_f32 v59, v59, v16, v17
	v_max3_f32 v59, v59, v18, v19
	v_max3_f32 v59, v59, v20, v21
	v_max3_f32 v59, v59, v22, v23
	v_max3_f32 v59, v59, v24, v25
	v_max3_f32 v59, v59, v26, v27
	v_max3_f32 v59, v59, v28, v29
	v_max3_f32 v59, v59, v30, v31
	v_mov_b32_e32 v60, v59
	s_nop 1
	v_permlane32_swap_b32_e32 v59, v60
	v_max_f32_e32 v60, v60, v60
	v_max_f32_e32 v59, v59, v59
	v_max_f32_e32 v235, v59, v60
	v_sub_f32_e32 v75, v21, v235
	v_sub_f32_e32 v74, v20, v235
	v_sub_f32_e32 v79, v17, v235
	v_sub_f32_e32 v78, v16, v235
	v_lshl_add_u64 v[16:17], s[22:23], 0, v[50:51]
	v_lshl_add_u64 v[20:21], s[22:23], 0, v[52:53]
	v_sub_f32_e32 v32, v32, v235
	v_lshl_add_u64 v[16:17], v[16:17], 0, v[180:181]
	v_lshl_add_u64 v[20:21], v[20:21], 0, v[180:181]
	v_sub_f32_e32 v33, v33, v235
	v_sub_f32_e32 v69, v27, v235
	v_sub_f32_e32 v68, v26, v235
	v_sub_f32_e32 v71, v25, v235
	v_sub_f32_e32 v70, v24, v235
	v_sub_f32_e32 v77, v19, v235
	v_sub_f32_e32 v76, v18, v235
	v_exp_f32_e32 v120, v32
	global_load_dwordx4 v[16:19], v[16:17], off
	v_add_co_u32_e32 v32, vcc, s68, v54
	global_load_dwordx4 v[24:27], v[20:21], off
	v_lshl_add_u64 v[20:21], s[6:7], 0, v[50:51]
	v_sub_f32_e32 v34, v34, v235
	v_sub_f32_e32 v35, v35, v235
	v_sub_f32_e32 v67, v29, v235
	v_sub_f32_e32 v66, v28, v235
	v_exp_f32_e32 v121, v33
	v_lshl_add_u64 v[20:21], v[20:21], 0, v[180:181]
	v_lshl_add_u64 v[28:29], s[6:7], 0, v[52:53]
	v_addc_co_u32_e32 v33, vcc, 0, v55, vcc
	v_sub_f32_e32 v73, v23, v235
	v_sub_f32_e32 v72, v22, v235
	v_exp_f32_e32 v122, v34
	v_exp_f32_e32 v124, v35
	global_load_dwordx4 v[20:23], v[20:21], off
	v_lshl_add_u64 v[28:29], v[28:29], 0, v[180:181]
	global_load_dwordx4 v[32:35], v[32:33], off
	v_sub_f32_e32 v65, v31, v235
	v_sub_f32_e32 v64, v30, v235
	global_load_dwordx4 v[28:31], v[28:29], off
	v_sub_f32_e32 v36, v36, v235
	v_sub_f32_e32 v37, v37, v235
	v_sub_f32_e32 v38, v38, v235
	v_sub_f32_e32 v39, v39, v235
	v_sub_f32_e32 v40, v40, v235
	v_sub_f32_e32 v41, v41, v235
	v_sub_f32_e32 v42, v42, v235
	v_sub_f32_e32 v43, v43, v235
	v_sub_f32_e32 v44, v44, v235
	v_sub_f32_e32 v45, v45, v235
	v_sub_f32_e32 v46, v46, v235
	v_sub_f32_e32 v47, v47, v235
	v_exp_f32_e32 v125, v36
	v_exp_f32_e32 v127, v37
	v_exp_f32_e32 v123, v38
	v_exp_f32_e32 v126, v39
	v_exp_f32_e32 v112, v40
	v_exp_f32_e32 v114, v41
	v_exp_f32_e32 v115, v42
	v_exp_f32_e32 v118, v43
	v_exp_f32_e32 v113, v44
	v_exp_f32_e32 v116, v45
	v_exp_f32_e32 v117, v46
	v_exp_f32_e32 v119, v47
	s_waitcnt vmcnt(0)
	s_waitcnt vmcnt(4)
	ds_write_b128 v211, v[16:19] offset:16384
	s_waitcnt vmcnt(3)
	ds_write_b128 v212, v[24:27] offset:16384
	s_waitcnt vmcnt(2)
	ds_write_b128 v213, v[20:23] offset:49152
	s_waitcnt vmcnt(0)
	ds_write_b128 v214, v[28:31] offset:49152
	v_lshlrev_b32_e32 v16, 11, v48
	v_and_b32_e32 v180, 0x7800, v16
	ds_write_b128 v239, v[32:35]
	v_cmp_gt_u32_e64 s[6:7], 32, v57
	v_mov_b64_e32 v[196:197], v[180:181]
	v_and_b32_e32 v180, 0x3c0, v194
	v_mov_b64_e32 v[62:63], v[14:15]
	v_mov_b64_e32 v[46:47], v[14:15]
	v_mov_b64_e32 v[30:31], v[14:15]
	v_mov_b64_e32 v[198:199], v[180:181]
	v_mov_b64_e32 v[60:61], v[12:13]
	v_mov_b64_e32 v[58:59], v[10:11]
	v_mov_b64_e32 v[56:57], v[8:9]
	v_mov_b64_e32 v[54:55], v[6:7]
	v_mov_b64_e32 v[52:53], v[4:5]
	v_mov_b64_e32 v[50:51], v[2:3]
	v_mov_b64_e32 v[48:49], v[0:1]
	v_mov_b64_e32 v[44:45], v[12:13]
	v_mov_b64_e32 v[42:43], v[10:11]
	v_mov_b64_e32 v[40:41], v[8:9]
	v_mov_b64_e32 v[38:39], v[6:7]
	v_mov_b64_e32 v[36:37], v[4:5]
	v_mov_b64_e32 v[34:35], v[2:3]
	v_mov_b64_e32 v[32:33], v[0:1]
	v_mov_b64_e32 v[28:29], v[12:13]
	v_mov_b64_e32 v[26:27], v[10:11]
	v_mov_b64_e32 v[24:25], v[8:9]
	v_mov_b64_e32 v[22:23], v[6:7]
	v_mov_b64_e32 v[20:21], v[4:5]
	v_mov_b64_e32 v[18:19], v[2:3]
	v_mov_b64_e32 v[16:17], v[0:1]
	s_waitcnt lgkmcnt(0)
	s_barrier
	v_lshlrev_b32_e32 v180, 1, v182
	v_lshlrev_b32_e32 v200, 1, v188
	v_mov_b32_e32 v201, v181
	v_lshl_add_u32 v190, v190, 1, v180
	v_lshl_add_u32 v192, v192, 1, v180
	v_lshl_add_u32 v194, v194, 1, v200
	v_lshl_add_u32 v196, v196, 1, v180
	v_lshl_add_u32 v198, v198, 1, v200
.LBB0_122:
	s_add_i32 s8, s40, s36
	ds_read_b128 v[160:163], v215 offset:49152
	ds_read_b128 v[164:167], v215 offset:57344
	v_xor_b32_e32 v80, 0x80000000, v235
	v_mov_b32_e32 v81, v80
	v_mov_b32_e32 v82, v80
	v_mov_b32_e32 v83, v80
	v_mov_b32_e32 v84, v80
	v_mov_b32_e32 v85, v80
	v_mov_b32_e32 v86, v80
	v_mov_b32_e32 v87, v80
	v_mov_b32_e32 v88, v80
	v_mov_b32_e32 v89, v80
	v_mov_b32_e32 v90, v80
	v_mov_b32_e32 v91, v80
	v_mov_b32_e32 v92, v80
	v_mov_b32_e32 v93, v80
	v_mov_b32_e32 v94, v80
	v_mov_b32_e32 v95, v80
	s_add_i32 s9, 0, 0x12000
	v_exp_f32_e32 v78, v78
	s_waitcnt lgkmcnt(1)
	v_mfma_f32_32x32x16_bf16 v[96:111], v[160:163], v[128:131], v[80:95]
	v_exp_f32_e32 v79, v79
	v_exp_f32_e32 v76, v76
	v_exp_f32_e32 v77, v77
	v_exp_f32_e32 v74, v74
	v_exp_f32_e32 v75, v75
	s_waitcnt lgkmcnt(0)
	v_mfma_f32_32x32x16_bf16 v[80:95], v[164:167], v[128:131], v[80:95]
	ds_read_b128 v[160:163], v216 offset:49152
	ds_read_b128 v[164:167], v216 offset:57344
	s_waitcnt lgkmcnt(1)
	v_mfma_f32_32x32x16_bf16 v[96:111], v[160:163], v[132:135], v[96:111]
	ds_read_b128 v[160:163], v217 offset:49152
	s_waitcnt lgkmcnt(1)
	v_mfma_f32_32x32x16_bf16 v[80:95], v[164:167], v[132:135], v[80:95]
	ds_read_b128 v[164:167], v217 offset:57344
	s_waitcnt lgkmcnt(1)
	v_mfma_f32_32x32x16_bf16 v[96:111], v[160:163], v[136:139], v[96:111]
	ds_read_b128 v[160:163], v218 offset:49152
	s_waitcnt lgkmcnt(1)
	v_mfma_f32_32x32x16_bf16 v[80:95], v[164:167], v[136:139], v[80:95]
	ds_read_b128 v[164:167], v218 offset:57344
	s_waitcnt lgkmcnt(1)
	v_mfma_f32_32x32x16_bf16 v[96:111], v[160:163], v[140:143], v[96:111]
	ds_read_b128 v[160:163], v219 offset:49152
	s_waitcnt lgkmcnt(1)
	v_mfma_f32_32x32x16_bf16 v[80:95], v[164:167], v[140:143], v[80:95]
	ds_read_b128 v[164:167], v219 offset:57344
	s_waitcnt lgkmcnt(1)
	v_mfma_f32_32x32x16_bf16 v[96:111], v[160:163], v[144:147], v[96:111]
	ds_read_b128 v[160:163], v220 offset:49152
	s_waitcnt lgkmcnt(1)
	v_mfma_f32_32x32x16_bf16 v[80:95], v[164:167], v[144:147], v[80:95]
	ds_read_b128 v[164:167], v220 offset:57344
	s_waitcnt lgkmcnt(1)
	v_mfma_f32_32x32x16_bf16 v[96:111], v[160:163], v[148:151], v[96:111]
	ds_read_b128 v[160:163], v221 offset:49152
	s_waitcnt lgkmcnt(1)
	v_mfma_f32_32x32x16_bf16 v[80:95], v[164:167], v[148:151], v[80:95]
	ds_read_b128 v[164:167], v221 offset:57344
	s_waitcnt lgkmcnt(1)
	v_mfma_f32_32x32x16_bf16 v[96:111], v[160:163], v[152:155], v[96:111]
	ds_read_b128 v[160:163], v222 offset:49152
	s_waitcnt lgkmcnt(1)
	v_mfma_f32_32x32x16_bf16 v[80:95], v[164:167], v[152:155], v[80:95]
	ds_read_b128 v[164:167], v222 offset:57344
	ds_read_b128 v[168:171], v224 offset:8192
	ds_read_b128 v[172:175], v224 offset:12288
	ds_read_b128 v[176:179], v225
	s_waitcnt lgkmcnt(4)
	v_mfma_f32_32x32x16_bf16 v[96:111], v[160:163], v[156:159], v[96:111]
	ds_read_b128 v[160:163], v227 offset:8192
	s_waitcnt lgkmcnt(4)
	v_mfma_f32_32x32x16_bf16 v[80:95], v[164:167], v[156:159], v[80:95]
	ds_read_b128 v[164:167], v227 offset:12288
	s_waitcnt lgkmcnt(2)
	v_mfma_f32_32x32x16_bf16 v[96:111], v[168:171], v[176:179], v[96:111]
	v_mfma_f32_32x32x16_bf16 v[80:95], v[172:175], v[176:179], v[80:95]
	ds_read_b128 v[168:171], v228
	ds_read_b128 v[172:175], v230 offset:8192
	ds_read_b128 v[176:179], v230 offset:12288
	s_waitcnt lgkmcnt(2)
	v_mfma_f32_32x32x16_bf16 v[96:111], v[160:163], v[168:171], v[96:111]
	v_mfma_f32_32x32x16_bf16 v[80:95], v[164:167], v[168:171], v[80:95]
	ds_read_b128 v[160:163], v231
	ds_read_b128 v[164:167], v233 offset:8192
	ds_read_b128 v[168:171], v233 offset:12288
	s_waitcnt lgkmcnt(2)
	v_mfma_f32_32x32x16_bf16 v[96:111], v[172:175], v[160:163], v[96:111]
	v_mfma_f32_32x32x16_bf16 v[80:95], v[176:179], v[160:163], v[80:95]
	ds_read_b128 v[172:175], v234
	s_waitcnt lgkmcnt(0)
	v_mfma_f32_32x32x16_bf16 v[96:111], v[164:167], v[172:175], v[96:111]
	v_exp_f32_e32 v160, v72
	v_exp_f32_e32 v161, v73
	v_exp_f32_e32 v162, v70
	v_exp_f32_e32 v163, v71
	v_cvt_pk_bf16_f32 v70, v113, v116
	v_cvt_pk_bf16_f32 v71, v117, v119
	v_cvt_pk_bf16_f32 v72, v78, v79
	v_mfma_f32_32x32x16_bf16 v[80:95], v[168:171], v[172:175], v[80:95]
	v_exp_f32_e32 v168, v64
	v_add_f32_e32 v64, 0, v120
	v_add_f32_e32 v64, v121, v64
	v_add_f32_e32 v64, v122, v64
	v_add_f32_e32 v64, v124, v64
	v_add_f32_e32 v64, v125, v64
	v_add_f32_e32 v64, v127, v64
	v_add_f32_e32 v64, v123, v64
	v_add_f32_e32 v64, v126, v64
	v_add_f32_e32 v64, v112, v64
	v_add_f32_e32 v64, v114, v64
	v_add_f32_e32 v64, v115, v64
	v_add_f32_e32 v64, v118, v64
	v_add_f32_e32 v64, v113, v64
	v_add_f32_e32 v64, v116, v64
	v_add_f32_e32 v64, v117, v64
	v_add_f32_e32 v64, v119, v64
	v_add_f32_e32 v64, v78, v64
	v_add_f32_e32 v64, v79, v64
	v_add_f32_e32 v64, v76, v64
	v_add_f32_e32 v64, v77, v64
	v_add_f32_e32 v64, v74, v64
	v_add_f32_e32 v64, v75, v64
	v_exp_f32_e32 v164, v68
	v_add_f32_e32 v64, v160, v64
	v_exp_f32_e32 v165, v69
	v_add_f32_e32 v64, v161, v64
	v_exp_f32_e32 v166, v66
	v_add_f32_e32 v64, v162, v64
	v_exp_f32_e32 v167, v67
	v_add_f32_e32 v64, v163, v64
	v_add_f32_e32 v64, v164, v64
	v_exp_f32_e32 v169, v65
	v_add_f32_e32 v64, v165, v64
	v_add_f32_e32 v64, v166, v64
	v_add_f32_e32 v64, v167, v64
	v_add_f32_e32 v64, v168, v64
	v_add_f32_e32 v242, v169, v64
	v_mov_b32_e32 v243, v242
	v_cvt_pk_bf16_f32 v64, v120, v121
	v_cvt_pk_bf16_f32 v65, v122, v124
	v_cvt_pk_bf16_f32 v66, v125, v127
	v_cvt_pk_bf16_f32 v67, v123, v126
	v_cvt_pk_bf16_f32 v68, v112, v114
	v_cvt_pk_bf16_f32 v69, v115, v118
	v_cvt_pk_bf16_f32 v73, v76, v77
	v_cvt_pk_bf16_f32 v74, v74, v75
	v_cvt_pk_bf16_f32 v75, v160, v161
	v_cvt_pk_bf16_f32 v76, v162, v163
	v_cvt_pk_bf16_f32 v77, v164, v165
	v_cvt_pk_bf16_f32 v78, v166, v167
	v_cvt_pk_bf16_f32 v79, v168, v169
	v_permlane32_swap_b32_e32 v242, v243
	v_permlane32_swap_b32_e32 v64, v66
	v_permlane32_swap_b32_e32 v65, v67
	v_permlane32_swap_b32_e32 v68, v70
	v_permlane32_swap_b32_e32 v69, v71
	v_permlane32_swap_b32_e32 v72, v74
	v_permlane32_swap_b32_e32 v73, v75
	v_permlane32_swap_b32_e32 v76, v78
	v_permlane32_swap_b32_e32 v77, v79
	s_cmp_eq_u32 s8, 0
	s_cselect_b64 s[8:9], -1, 0
	s_add_u32 s41, s18, s38
	s_addc_u32 s42, s19, s39
	s_add_u32 s20, s18, s10
	s_addc_u32 s21, s19, s11
	s_and_b64 vcc, exec, s[8:9]
	s_cbranch_vccnz .Lmla_sl_last
	s_add_u32 s22, s41, 0x64c2400
	s_addc_u32 s23, s42, 0
	s_add_u32 s44, s41, 0x64c2500
	s_addc_u32 s45, s42, 0
	global_load_dwordx4 v[160:163], v190, s[44:45]
	global_load_dwordx4 v[164:167], v192, s[44:45]
	global_load_dwordx4 v[168:171], v190, s[22:23]
	global_load_dwordx4 v[172:175], v192, s[22:23]
	s_add_u32 s44, s20, 0x28f26400
	s_addc_u32 s45, s21, 0
	global_load_dwordx4 v[176:179], v194, s[44:45]
	s_branch .Lmla_sl_merge
.Lmla_sl_last:
	s_mov_b32 s44, s27
	s_mov_b32 s45, s66
	global_load_dwordx4 v[160:163], v196, s[44:45]
	global_load_dwordx4 v[164:167], v196, s[44:45]
	global_load_dwordx4 v[168:171], v196, s[4:5]
	global_load_dwordx4 v[172:175], v196, s[4:5]
	s_mov_b32 s44, s96
	s_mov_b32 s45, s60
	global_load_dwordx4 v[176:179], v198, s[44:45]
.Lmla_sl_merge:
	ds_read_b64_tr_b16 v[112:113], v187 offset:0
	ds_read_b64_tr_b16 v[114:115], v187 offset:0x800
	ds_read_b64_tr_b16 v[116:117], v187 offset:0x1000
	ds_read_b64_tr_b16 v[118:119], v187 offset:0x1800
	ds_read_b64_tr_b16 v[120:121], v187 offset:0x2000
	ds_read_b64_tr_b16 v[122:123], v187 offset:0x2800
	ds_read_b64_tr_b16 v[124:125], v187 offset:0x3000
	ds_read_b64_tr_b16 v[126:127], v187 offset:0x3800
	s_nop 0
	s_waitcnt lgkmcnt(4)
	v_mfma_f32_32x32x16_bf16 v[16:31], v[64:67], v[112:115], v[16:31]
	ds_read_b64_tr_b16 v[112:113], v187 offset:0x200
	ds_read_b64_tr_b16 v[114:115], v187 offset:0xa00
	v_mfma_f32_32x32x16_bf16 v[16:31], v[68:71], v[116:119], v[16:31]
	ds_read_b64_tr_b16 v[116:117], v187 offset:0x1200
	ds_read_b64_tr_b16 v[118:119], v187 offset:0x1a00
	s_waitcnt lgkmcnt(4)
	v_mfma_f32_32x32x16_bf16 v[16:31], v[72:75], v[120:123], v[16:31]
	ds_read_b64_tr_b16 v[120:121], v187 offset:0x2200
	ds_read_b64_tr_b16 v[122:123], v187 offset:0x2a00
	v_mfma_f32_32x32x16_bf16 v[16:31], v[76:79], v[124:127], v[16:31]
	ds_read_b64_tr_b16 v[124:125], v187 offset:0x3200
	ds_read_b64_tr_b16 v[126:127], v187 offset:0x3a00
	s_waitcnt lgkmcnt(4)
	v_mfma_f32_32x32x16_bf16 v[32:47], v[64:67], v[112:115], v[32:47]
	ds_read_b64_tr_b16 v[112:113], v187 offset:0x400
	ds_read_b64_tr_b16 v[114:115], v187 offset:0xc00
	v_mfma_f32_32x32x16_bf16 v[32:47], v[68:71], v[116:119], v[32:47]
	ds_read_b64_tr_b16 v[116:117], v187 offset:0x1400
	ds_read_b64_tr_b16 v[118:119], v187 offset:0x1c00
	s_waitcnt lgkmcnt(4)
	v_mfma_f32_32x32x16_bf16 v[32:47], v[72:75], v[120:123], v[32:47]
	ds_read_b64_tr_b16 v[120:121], v187 offset:0x2400
	ds_read_b64_tr_b16 v[122:123], v187 offset:0x2c00
	v_mfma_f32_32x32x16_bf16 v[32:47], v[76:79], v[124:127], v[32:47]
	ds_read_b64_tr_b16 v[124:125], v187 offset:0x3400
	ds_read_b64_tr_b16 v[126:127], v187 offset:0x3c00
	s_waitcnt lgkmcnt(4)
	v_mfma_f32_32x32x16_bf16 v[48:63], v[64:67], v[112:115], v[48:63]
	ds_read_b64_tr_b16 v[112:113], v187 offset:0x600
	ds_read_b64_tr_b16 v[114:115], v187 offset:0xe00
	v_mfma_f32_32x32x16_bf16 v[48:63], v[68:71], v[116:119], v[48:63]
	ds_read_b64_tr_b16 v[116:117], v187 offset:0x1600
	ds_read_b64_tr_b16 v[118:119], v187 offset:0x1e00
	s_waitcnt lgkmcnt(4)
	v_mfma_f32_32x32x16_bf16 v[48:63], v[72:75], v[120:123], v[48:63]
	ds_read_b64_tr_b16 v[120:121], v187 offset:0x2600
	ds_read_b64_tr_b16 v[122:123], v187 offset:0x2e00
	v_mfma_f32_32x32x16_bf16 v[48:63], v[76:79], v[124:127], v[48:63]
	ds_read_b64_tr_b16 v[124:125], v187 offset:0x3600
	ds_read_b64_tr_b16 v[126:127], v187 offset:0x3e00
	s_waitcnt lgkmcnt(4)
	v_mfma_f32_32x32x16_bf16 v[0:15], v[64:67], v[112:115], v[0:15]
	v_max_f32_e32 v64, v97, v97
	v_max_f32_e32 v65, v96, v96
	v_max_f32_e32 v64, v65, v64
	v_max3_f32 v64, v64, v98, v99
	v_max3_f32 v64, v64, v100, v101
	v_max3_f32 v64, v64, v102, v103
	v_max3_f32 v64, v64, v104, v105
	v_mfma_f32_32x32x16_bf16 v[0:15], v[68:71], v[116:119], v[0:15]
	v_max3_f32 v64, v64, v106, v107
	v_max3_f32 v64, v64, v108, v109
	v_max3_f32 v64, v64, v110, v111
	v_max3_f32 v64, v64, v80, v81
	v_max3_f32 v64, v64, v82, v83
	v_max3_f32 v64, v64, v84, v85
	v_max3_f32 v64, v64, v86, v87
	s_waitcnt lgkmcnt(0)
	v_mfma_f32_32x32x16_bf16 v[0:15], v[72:75], v[120:123], v[0:15]
	v_max3_f32 v64, v64, v88, v89
	v_max3_f32 v64, v64, v90, v91
	v_max3_f32 v64, v64, v92, v93
	v_max3_f32 v64, v64, v94, v95
	v_mov_b32_e32 v65, v64
	s_nop 1
	v_permlane32_swap_b32_e32 v64, v65
	v_mfma_f32_32x32x16_bf16 v[0:15], v[76:79], v[124:127], v[0:15]
	v_max_f32_e32 v65, v65, v65
	v_max_f32_e32 v64, v64, v64
	v_max_f32_e32 v64, v64, v65
	v_cmp_ge_f32_e32 vcc, s63, v64
	s_cmp_eq_u64 vcc, exec
	v_mov_b32_e32 v244, 1.0
	s_cbranch_scc0 .LBB0_140

.LBB0_129:
	v_exp_f32_e32 v73, v96
	v_exp_f32_e32 v75, v97
	v_exp_f32_e32 v76, v98
	v_exp_f32_e32 v77, v99
	v_exp_f32_e32 v78, v100
	v_exp_f32_e32 v79, v101
	v_exp_f32_e32 v72, v102
	v_exp_f32_e32 v74, v103
	v_exp_f32_e32 v66, v104
	v_exp_f32_e32 v67, v105
	v_exp_f32_e32 v68, v106
	v_exp_f32_e32 v69, v110
	v_exp_f32_e32 v71, v107
	v_exp_f32_e32 v64, v108
	v_exp_f32_e32 v65, v109
	v_exp_f32_e32 v70, v111
	s_waitcnt lgkmcnt(0)
	s_barrier
	ds_read_b128 v[246:249], v215 offset:32768
	ds_read_b128 v[250:253], v215 offset:40960
	v_xor_b32_e32 v112, 0x80000000, v235
	v_mov_b32_e32 v113, v112
	v_mov_b32_e32 v114, v112
	v_mov_b32_e32 v115, v112
	v_mov_b32_e32 v116, v112
	v_mov_b32_e32 v117, v112
	v_mov_b32_e32 v118, v112
	v_mov_b32_e32 v119, v112
	v_mov_b32_e32 v120, v112
	v_mov_b32_e32 v121, v112
	v_mov_b32_e32 v122, v112
	v_mov_b32_e32 v123, v112
	v_mov_b32_e32 v124, v112
	v_mov_b32_e32 v125, v112
	v_mov_b32_e32 v126, v112
	v_mov_b32_e32 v127, v112
	v_exp_f32_e32 v189, v80
	v_add_f32_e32 v80, 0, v73
	s_waitcnt lgkmcnt(1)
	v_mfma_f32_32x32x16_bf16 v[96:111], v[246:249], v[128:131], v[112:127]
	v_add_f32_e32 v80, v75, v80
	v_add_f32_e32 v80, v76, v80
	v_add_f32_e32 v80, v77, v80
	v_add_f32_e32 v80, v78, v80
	v_add_f32_e32 v80, v79, v80
	v_add_f32_e32 v80, v72, v80
	v_add_f32_e32 v80, v74, v80
	s_waitcnt lgkmcnt(0)
	v_mfma_f32_32x32x16_bf16 v[112:127], v[250:253], v[128:131], v[112:127]
	ds_read_b128 v[246:249], v216 offset:32768
	ds_read_b128 v[250:253], v216 offset:40960
	v_add_f32_e32 v80, v66, v80
	v_add_f32_e32 v80, v67, v80
	v_add_f32_e32 v80, v68, v80
	v_add_f32_e32 v80, v71, v80
	v_add_f32_e32 v80, v64, v80
	v_exp_f32_e32 v201, v81
	s_waitcnt lgkmcnt(1)
	v_mfma_f32_32x32x16_bf16 v[96:111], v[246:249], v[132:135], v[96:111]
	v_add_f32_e32 v80, v65, v80
	v_add_f32_e32 v80, v69, v80
	v_add_f32_e32 v80, v70, v80
	v_exp_f32_e32 v84, v84
	v_add_f32_e32 v80, v189, v80
	v_exp_f32_e32 v85, v85
	v_add_f32_e32 v80, v201, v80
	s_waitcnt lgkmcnt(0)
	v_mfma_f32_32x32x16_bf16 v[112:127], v[250:253], v[132:135], v[112:127]
	ds_read_b128 v[246:249], v217 offset:32768
	ds_read_b128 v[250:253], v217 offset:40960
	v_exp_f32_e32 v86, v86
	v_exp_f32_e32 v87, v87
	v_exp_f32_e32 v90, v90
	v_exp_f32_e32 v91, v91
	v_exp_f32_e32 v92, v92
	v_exp_f32_e32 v93, v93
	s_waitcnt lgkmcnt(1)
	v_mfma_f32_32x32x16_bf16 v[96:111], v[246:249], v[136:139], v[96:111]
	v_exp_f32_e32 v94, v94
	v_exp_f32_e32 v95, v95
	v_cvt_pk_bf16_f32 v81, v76, v77
	v_cvt_pk_bf16_f32 v66, v66, v67
	v_cvt_pk_bf16_f32 v67, v68, v71
	v_cvt_pk_bf16_f32 v68, v64, v65
	v_cvt_pk_bf16_f32 v69, v69, v70
	s_waitcnt lgkmcnt(0)
	v_mfma_f32_32x32x16_bf16 v[112:127], v[250:253], v[136:139], v[112:127]
	ds_read_b128 v[246:249], v218 offset:32768
	ds_read_b128 v[250:253], v218 offset:40960
	v_cvt_pk_bf16_f32 v77, v90, v91
	v_permlane32_swap_b32_e32 v66, v68
	v_permlane32_swap_b32_e32 v67, v69
	s_waitcnt lgkmcnt(1)
	v_mfma_f32_32x32x16_bf16 v[96:111], v[246:249], v[140:143], v[96:111]
	s_waitcnt lgkmcnt(0)
	v_mfma_f32_32x32x16_bf16 v[112:127], v[250:253], v[140:143], v[112:127]
	ds_read_b128 v[246:249], v219 offset:32768
	ds_read_b128 v[250:253], v219 offset:40960
	s_waitcnt lgkmcnt(1)
	v_mfma_f32_32x32x16_bf16 v[96:111], v[246:249], v[144:147], v[96:111]
	ds_read_b128 v[246:249], v220 offset:32768
	s_waitcnt lgkmcnt(1)
	v_mfma_f32_32x32x16_bf16 v[112:127], v[250:253], v[144:147], v[112:127]
	ds_read_b128 v[250:253], v220 offset:40960
	s_waitcnt lgkmcnt(1)
	v_mfma_f32_32x32x16_bf16 v[96:111], v[246:249], v[148:151], v[96:111]
	ds_read_b128 v[246:249], v221 offset:32768
	s_waitcnt lgkmcnt(1)
	v_mfma_f32_32x32x16_bf16 v[112:127], v[250:253], v[148:151], v[112:127]
	ds_read_b128 v[250:253], v221 offset:40960
	s_waitcnt lgkmcnt(1)
	v_mfma_f32_32x32x16_bf16 v[96:111], v[246:249], v[152:155], v[96:111]
	ds_read_b128 v[246:249], v222 offset:32768
	s_waitcnt lgkmcnt(1)
	v_mfma_f32_32x32x16_bf16 v[112:127], v[250:253], v[152:155], v[112:127]
	ds_read_b128 v[250:253], v222 offset:40960
	ds_read_b128 v[160:163], v224
	ds_read_b128 v[164:167], v224 offset:4096
	ds_read_b128 v[206:209], v225
	s_waitcnt lgkmcnt(4)
	v_mfma_f32_32x32x16_bf16 v[96:111], v[246:249], v[156:159], v[96:111]
	ds_read_b128 v[246:249], v227
	s_waitcnt lgkmcnt(4)
	v_mfma_f32_32x32x16_bf16 v[112:127], v[250:253], v[156:159], v[112:127]
	ds_read_b128 v[250:253], v227 offset:4096
	s_waitcnt lgkmcnt(2)
	v_mfma_f32_32x32x16_bf16 v[96:111], v[160:163], v[206:209], v[96:111]
	v_mfma_f32_32x32x16_bf16 v[112:127], v[164:167], v[206:209], v[112:127]
	ds_read_b128 v[160:163], v228
	ds_read_b128 v[164:167], v230
	ds_read_b128 v[206:209], v230 offset:4096
	s_waitcnt lgkmcnt(2)
	v_mfma_f32_32x32x16_bf16 v[96:111], v[246:249], v[160:163], v[96:111]
	v_mfma_f32_32x32x16_bf16 v[112:127], v[250:253], v[160:163], v[112:127]
	ds_read_b128 v[246:249], v231
	ds_read_b128 v[250:253], v233
	ds_read_b128 v[160:163], v233 offset:4096
	s_waitcnt lgkmcnt(2)
	v_mfma_f32_32x32x16_bf16 v[96:111], v[164:167], v[246:249], v[96:111]
	v_mfma_f32_32x32x16_bf16 v[112:127], v[206:209], v[246:249], v[112:127]
	ds_read_b128 v[164:167], v234
	s_waitcnt lgkmcnt(0)
	v_mfma_f32_32x32x16_bf16 v[96:111], v[250:253], v[164:167], v[96:111]
	v_exp_f32_e32 v206, v82
	v_exp_f32_e32 v207, v83
	v_exp_f32_e32 v208, v88
	v_exp_f32_e32 v209, v89
	v_add_f32_e32 v80, v206, v80
	v_add_f32_e32 v80, v207, v80
	v_add_f32_e32 v80, v84, v80
	v_add_f32_e32 v80, v85, v80
	v_add_f32_e32 v80, v86, v80
	v_add_f32_e32 v80, v87, v80
	v_add_f32_e32 v80, v208, v80
	v_add_f32_e32 v80, v209, v80
	v_mfma_f32_32x32x16_bf16 v[112:127], v[160:163], v[164:167], v[112:127]
	v_add_f32_e32 v80, v90, v80
	v_add_f32_e32 v80, v91, v80
	v_add_f32_e32 v80, v92, v80
	v_add_f32_e32 v80, v93, v80
	v_add_f32_e32 v80, v94, v80
	v_add_f32_e32 v88, v95, v80
	v_mov_b32_e32 v89, v88
	v_cvt_pk_bf16_f32 v80, v73, v75
	v_cvt_pk_bf16_f32 v82, v78, v79
	v_cvt_pk_bf16_f32 v83, v72, v74
	v_cvt_pk_bf16_f32 v72, v189, v201
	v_cvt_pk_bf16_f32 v73, v206, v207
	v_cvt_pk_bf16_f32 v74, v84, v85
	v_cvt_pk_bf16_f32 v75, v86, v87
	v_cvt_pk_bf16_f32 v76, v208, v209
	v_cvt_pk_bf16_f32 v78, v92, v93
	v_cvt_pk_bf16_f32 v79, v94, v95
	v_permlane32_swap_b32_e32 v88, v89
	v_permlane32_swap_b32_e32 v80, v82
	v_permlane32_swap_b32_e32 v81, v83
	v_permlane32_swap_b32_e32 v72, v74
	v_permlane32_swap_b32_e32 v73, v75
	v_permlane32_swap_b32_e32 v76, v78
	v_permlane32_swap_b32_e32 v77, v79
	s_add_i32 s43, s36, 1
	s_cmp_le_u32 s43, s25
	s_cselect_b64 s[22:23], -1, 0
	s_cmp_gt_u32 s43, s25
	s_cbranch_scc1 .LBB0_131
	s_add_u32 s44, s41, 0x6502400
	s_addc_u32 s45, s42, 0
	s_add_u32 s46, s41, 0x6502500
	s_addc_u32 s47, s42, 0
	global_load_dwordx4 v[160:163], v190, s[46:47]
	global_load_dwordx4 v[164:167], v192, s[46:47]
	global_load_dwordx4 v[168:171], v190, s[44:45]
	global_load_dwordx4 v[172:175], v192, s[44:45]
	s_add_u32 s44, s20, 0x28f28400
	s_addc_u32 s45, s21, 0
	global_load_dwordx4 v[176:179], v194, s[44:45]
